# nt hint on the 8 once-read f32 x loads of the P0 x->bf16 pass
# speedup vs baseline: 1.0110x; 1.0110x over previous
; __host__ __device__ __forceinline__ int blk_off(int r, int c) { const int rr = r & 127; return (r >> 7) * 8192 + (((rr >> 4) * 2 + (c >> 5)) * 512) + (rr & 15) * 32 + (c & 31); }
; __device__ __forceinline__ unsigned pk2(float lo, float hi) { return f2bf(lo) | (f2bf(hi) << 16); }
; __global__ void __launch_bounds__(NWAVES * 64, 2) hybrid_fwd(Args args) {
;     ...
;         for (int row = gw; row < T; row += NGW) {
;             const f32x4* xr = (const f32x4*)(x + (size_t)row * D) + lane; float s = 0.f;
;             bf16* const xbrow = XB + (size_t)(row >> 8) * (D / 64) * (256 * 64);
; #pragma unroll
;             for (int j = 0; j < 8; ++j) { const f32x4 v = xr[64 * j]; s += (v[0] * v[0] + v[1] * v[1]) + (v[2] * v[2] + v[3] * v[3]);
;                 { const int col = 256 * j + 4 * lane; *(unsigned long long*)(xbrow + (size_t)(col >> 6) * (256 * 64) + pg8::blk_off(row & 255, col & 63)) = (unsigned long long)pk2(v[0], v[1]) | ((unsigned long long)pk2(v[2], v[3]) << 32); } }
;             s = wave_sum(s); if (lane < 32) ssq[(size_t)row * 32 + lane] = (lane == 0) ? s : 0.f;
;         }
.LBB0_140:
	s_waitcnt vmcnt(9)
	v_add_co_u32_e64 v28, s[6:7], s11, v10
	s_nop 1
	v_addc_co_u32_e64 v29, s[6:7], -1, v11, s[6:7]
	s_waitcnt lgkmcnt(0)
	global_load_dwordx4 v[2:5], v[28:29], off offset:-3072 nt
	s_ashr_i32 s6, s22, 8
	s_ashr_i32 s7, s6, 31
	s_lshl_b64 s[6:7], s[6:7], 20
	s_add_u32 s6, s3, s6
	s_addc_u32 s7, s10, s7
	s_lshl_b32 s24, s22, 6
	s_lshr_b32 s25, s22, 3
	s_lshl_b32 s27, s22, 5
	s_and_b32 s24, s24, 0x2000
	v_and_or_b32 v6, s25, 14, v16
	s_and_b32 s25, s27, 0x1e0
	v_lshl_or_b32 v6, v6, 9, s24
	v_or3_b32 v6, v6, s25, v1
	v_lshlrev_b32_e32 v6, 1, v6
	v_lshl_add_u64 v[14:15], s[6:7], 0, v[6:7]
	v_lshl_add_u64 v[14:15], v[14:15], 0, v[12:13]
	s_waitcnt vmcnt(9)
	v_add_co_u32_e64 v30, s[6:7], s14, v14
	s_waitcnt vmcnt(0)
	v_bfe_u32 v6, v2, 16, 1
	v_bfe_u32 v24, v4, 16, 1
	v_bfe_u32 v23, v3, 16, 1
	v_bfe_u32 v25, v5, 16, 1
	v_add3_u32 v6, v2, v6, s12
	v_add3_u32 v24, v4, v24, s12
	v_add3_u32 v23, v3, v23, s12
	v_add3_u32 v25, v5, v25, s12
	v_lshrrev_b32_e32 v6, 16, v6
	v_lshrrev_b32_e32 v26, 16, v24
	v_and_or_b32 v24, v23, s13, v6
	v_and_or_b32 v25, v25, s13, v26
	global_store_dwordx2 v[14:15], v[24:25], off
	global_load_dwordx4 v[24:27], v[28:29], off offset:-2048 nt
	v_addc_co_u32_e64 v31, s[6:7], 0, v15, s[6:7]
	v_mul_f32_e32 v3, v3, v3
	v_mul_f32_e32 v5, v5, v5
	v_fmac_f32_e32 v3, v2, v2
	v_fmac_f32_e32 v5, v4, v4
	v_add_f32_e32 v2, v3, v5
	s_waitcnt vmcnt(0)
	v_bfe_u32 v6, v24, 16, 1
	v_bfe_u32 v32, v26, 16, 1
	v_bfe_u32 v23, v25, 16, 1
	v_bfe_u32 v33, v27, 16, 1
	v_add3_u32 v6, v24, v6, s12
	v_add3_u32 v32, v26, v32, s12
	v_add3_u32 v23, v25, v23, s12
	v_add3_u32 v33, v27, v33, s12
	v_lshrrev_b32_e32 v6, 16, v6
	v_lshrrev_b32_e32 v34, 16, v32
	v_and_or_b32 v32, v23, s13, v6
	v_and_or_b32 v33, v33, s13, v34
	global_store_dwordx2 v[30:31], v[32:33], off
	global_load_dwordx4 v[28:31], v[28:29], off offset:-1024 nt
	v_add_co_u32_e64 v32, s[6:7], s15, v14
	v_mul_f32_e32 v3, v25, v25
	s_nop 0
	v_addc_co_u32_e64 v33, s[6:7], 0, v15, s[6:7]
	v_mul_f32_e32 v4, v27, v27
	v_fmac_f32_e32 v3, v24, v24
	v_fmac_f32_e32 v4, v26, v26
	v_add_f32_e32 v3, v3, v4
	v_add_f32_e32 v2, v2, v3
	s_waitcnt vmcnt(0)
	v_bfe_u32 v6, v28, 16, 1
	v_bfe_u32 v34, v30, 16, 1
	v_bfe_u32 v23, v29, 16, 1
	v_bfe_u32 v35, v31, 16, 1
	v_add3_u32 v6, v28, v6, s12
	v_add3_u32 v34, v30, v34, s12
	v_add3_u32 v23, v29, v23, s12
	v_add3_u32 v35, v31, v35, s12
	v_lshrrev_b32_e32 v6, 16, v6
	v_lshrrev_b32_e32 v36, 16, v34
	v_and_or_b32 v34, v23, s13, v6
	v_and_or_b32 v35, v35, s13, v36
	global_store_dwordx2 v[32:33], v[34:35], off
	global_load_dwordx4 v[32:35], v[10:11], off offset:-4096 nt
	v_add_co_u32_e64 v36, s[6:7], s16, v14
	v_mul_f32_e32 v3, v29, v29
	s_nop 0
	v_addc_co_u32_e64 v37, s[6:7], 0, v15, s[6:7]
	v_mul_f32_e32 v4, v31, v31
	v_fmac_f32_e32 v3, v28, v28
	v_fmac_f32_e32 v4, v30, v30
	v_add_f32_e32 v3, v3, v4
	v_add_f32_e32 v2, v2, v3
	s_waitcnt vmcnt(0)
	v_bfe_u32 v6, v32, 16, 1
	v_bfe_u32 v38, v34, 16, 1
	v_bfe_u32 v23, v33, 16, 1
	v_bfe_u32 v39, v35, 16, 1
	v_add3_u32 v6, v32, v6, s12
	v_add3_u32 v38, v34, v38, s12
	v_add3_u32 v23, v33, v23, s12
	v_add3_u32 v39, v35, v39, s12
	v_lshrrev_b32_e32 v6, 16, v6
	v_lshrrev_b32_e32 v40, 16, v38
	v_and_or_b32 v38, v23, s13, v6
	v_and_or_b32 v39, v39, s13, v40
	global_store_dwordx2 v[36:37], v[38:39], off
	global_load_dwordx4 v[36:39], v[10:11], off offset:-3072 nt
	v_add_co_u32_e64 v40, s[6:7], s17, v14
	v_mul_f32_e32 v3, v33, v33
	s_nop 0
	v_addc_co_u32_e64 v41, s[6:7], 0, v15, s[6:7]
	v_mul_f32_e32 v4, v35, v35
	v_fmac_f32_e32 v3, v32, v32
	v_fmac_f32_e32 v4, v34, v34
	v_add_f32_e32 v3, v3, v4
	v_add_f32_e32 v2, v2, v3
	s_waitcnt vmcnt(0)
	v_bfe_u32 v6, v36, 16, 1
	v_bfe_u32 v42, v38, 16, 1
	v_bfe_u32 v23, v37, 16, 1
	v_bfe_u32 v43, v39, 16, 1
	v_add3_u32 v6, v36, v6, s12
	v_add3_u32 v42, v38, v42, s12
	v_add3_u32 v23, v37, v23, s12
	v_add3_u32 v43, v39, v43, s12
	v_lshrrev_b32_e32 v6, 16, v6
	v_lshrrev_b32_e32 v44, 16, v42
	v_and_or_b32 v42, v23, s13, v6
	v_and_or_b32 v43, v43, s13, v44
	global_store_dwordx2 v[40:41], v[42:43], off
	global_load_dwordx4 v[40:43], v[10:11], off offset:-2048 nt
	v_add_co_u32_e64 v44, s[6:7], s18, v14
	v_mul_f32_e32 v3, v37, v37
	s_nop 0
	v_addc_co_u32_e64 v45, s[6:7], 0, v15, s[6:7]
	v_mul_f32_e32 v4, v39, v39
	v_fmac_f32_e32 v3, v36, v36
	v_fmac_f32_e32 v4, v38, v38
	v_add_f32_e32 v3, v3, v4
	v_add_f32_e32 v2, v2, v3
	s_waitcnt vmcnt(0)
	v_bfe_u32 v6, v40, 16, 1
	v_bfe_u32 v46, v42, 16, 1
	v_bfe_u32 v23, v41, 16, 1
	v_bfe_u32 v47, v43, 16, 1
	v_add3_u32 v6, v40, v6, s12
	v_add3_u32 v46, v42, v46, s12
	v_add3_u32 v23, v41, v23, s12
	v_add3_u32 v47, v43, v47, s12
	v_lshrrev_b32_e32 v6, 16, v6
	v_lshrrev_b32_e32 v48, 16, v46
	v_and_or_b32 v46, v23, s13, v6
	v_and_or_b32 v47, v47, s13, v48
	global_store_dwordx2 v[44:45], v[46:47], off
	global_load_dwordx4 v[44:47], v[10:11], off offset:-1024 nt
	v_add_co_u32_e64 v48, s[6:7], s19, v14
	v_mul_f32_e32 v3, v41, v41
	s_nop 0
	v_addc_co_u32_e64 v49, s[6:7], 0, v15, s[6:7]
	v_mul_f32_e32 v4, v43, v43
	v_fmac_f32_e32 v3, v40, v40
	v_fmac_f32_e32 v4, v42, v42
	v_add_f32_e32 v3, v3, v4
	v_add_f32_e32 v2, v2, v3
	v_add_co_u32_e64 v14, s[6:7], s23, v14
	s_waitcnt vmcnt(0)
	v_bfe_u32 v6, v44, 16, 1
	v_bfe_u32 v50, v46, 16, 1
	v_bfe_u32 v23, v45, 16, 1
	v_bfe_u32 v51, v47, 16, 1
	v_add3_u32 v6, v44, v6, s12
	v_add3_u32 v50, v46, v50, s12
	v_add3_u32 v23, v45, v23, s12
	v_add3_u32 v51, v47, v51, s12
	v_lshrrev_b32_e32 v6, 16, v6
	v_lshrrev_b32_e32 v52, 16, v50
	v_and_or_b32 v50, v23, s13, v6
	v_and_or_b32 v51, v51, s13, v52
	global_store_dwordx2 v[48:49], v[50:51], off
	global_load_dwordx4 v[48:51], v[10:11], off nt
	v_mul_f32_e32 v3, v45, v45
	v_mul_f32_e32 v4, v47, v47
	v_fmac_f32_e32 v3, v44, v44
	v_fmac_f32_e32 v4, v46, v46
	v_add_f32_e32 v3, v3, v4
	v_add_f32_e32 v2, v2, v3
	v_addc_co_u32_e64 v15, s[6:7], 0, v15, s[6:7]
	s_waitcnt vmcnt(0)
	v_mul_f32_e32 v3, v49, v49
	v_mul_f32_e32 v4, v51, v51
	v_fmac_f32_e32 v3, v48, v48
	v_fmac_f32_e32 v4, v50, v50
	v_add_f32_e32 v3, v3, v4
	v_add_f32_e32 v2, v2, v3
	ds_bpermute_b32 v3, v17, v2
	v_bfe_u32 v4, v48, 16, 1
	v_bfe_u32 v6, v50, 16, 1
	v_bfe_u32 v5, v49, 16, 1
	v_bfe_u32 v23, v51, 16, 1
	s_waitcnt lgkmcnt(0)
	v_add_f32_e32 v2, v2, v3
	ds_bpermute_b32 v3, v18, v2
	v_add3_u32 v4, v48, v4, s12
	v_add3_u32 v6, v50, v6, s12
	v_add3_u32 v5, v49, v5, s12
	v_add3_u32 v23, v51, v23, s12
	s_waitcnt lgkmcnt(0)
	v_add_f32_e32 v2, v2, v3
	ds_bpermute_b32 v3, v19, v2
	v_lshrrev_b32_e32 v4, 16, v4
	v_lshrrev_b32_e32 v6, 16, v6
	v_and_or_b32 v4, v5, s13, v4
	v_and_or_b32 v5, v23, s13, v6
	s_waitcnt lgkmcnt(0)
	v_add_f32_e32 v2, v2, v3
	ds_bpermute_b32 v3, v20, v2
	global_store_dwordx2 v[14:15], v[4:5], off
	s_waitcnt lgkmcnt(0)
	v_add_f32_e32 v2, v2, v3
	ds_bpermute_b32 v3, v21, v2
	s_waitcnt lgkmcnt(0)
	v_add_f32_e32 v2, v2, v3
	ds_bpermute_b32 v3, v22, v2
	s_and_saveexec_b64 s[6:7], vcc
	s_cbranch_execz .LBB0_139
	s_waitcnt lgkmcnt(0)
	v_add_f32_e32 v2, v2, v3
	v_cndmask_b32_e64 v2, 0, v2, s[4:5]
	global_store_dword v[8:9], v2, off
	s_branch .LBB0_139
